# rec_pass1 score blocks: all LDS reads of a block hoisted to its top into fresh registers (was read-wait-compute per pair)
# baseline (speedup 1.0000x reference)
.LBB0_200:
	s_or_b64 exec, exec, s[2:3]
	s_movk_i32 s2, 0x840
	v_mad_u32_u24 v12, v108, s2, v105
	v_add_u32_e32 v4, 0xffffff7c, v12
	v_cmp_eq_u32_e64 s[36:37], 0, v108
	v_cmp_ne_u32_e32 vcc, 0, v108
	v_mov_b32_e32 v25, 0
	v_lshl_add_u32 v14, v15, 2, v4
	v_mov_b32_e32 v26, 0
	s_and_saveexec_b64 s[2:3], vcc
	ds_read_b32 v26, v14
	s_or_b64 exec, exec, s[2:3]
	v_lshlrev_b32_e32 v13, 2, v15
	s_and_saveexec_b64 s[2:3], vcc
	s_movk_i32 s4, 0xff80
	v_add3_u32 v4, v12, v13, s4
	ds_read_b32 v25, v4
	s_or_b64 exec, exec, s[2:3]
	v_mul_u32_u24_e32 v4, 0x84, v110
	v_add3_u32 v11, v105, v4, v13
	ds_read2_b32 v[4:5], v11 offset1:1
	v_mov_b32_e32 v27, 0
	v_mov_b32_e32 v28, 0
	s_and_saveexec_b64 s[2:3], vcc
	ds_read_b32 v28, v14 offset:8
	s_or_b64 exec, exec, s[2:3]
	s_and_saveexec_b64 s[2:3], vcc
	s_movk_i32 s4, 0xff88
	v_add3_u32 v6, v12, v13, s4
	ds_read_b32 v27, v6
	s_or_b64 exec, exec, s[2:3]
	ds_read2_b32 v[6:7], v11 offset0:2 offset1:3
	v_mov_b32_e32 v20, 0
	v_mov_b32_e32 v21, 0
	s_and_saveexec_b64 s[2:3], vcc
	ds_read_b32 v21, v14 offset:16
	s_or_b64 exec, exec, s[2:3]
	s_and_saveexec_b64 s[2:3], vcc
	s_movk_i32 s4, 0xff90
	v_add3_u32 v8, v12, v13, s4
	ds_read_b32 v20, v8
	s_or_b64 exec, exec, s[2:3]
	ds_read2_b32 v[8:9], v11 offset0:4 offset1:5
	v_mov_b32_e32 v22, 0
	v_mov_b32_e32 v23, 0
	s_and_saveexec_b64 s[2:3], vcc
	ds_read_b32 v23, v14 offset:24
	s_or_b64 exec, exec, s[2:3]
	s_and_saveexec_b64 s[2:3], vcc
	s_movk_i32 s4, 0xff98
	v_add3_u32 v12, v12, v13, s4
	ds_read_b32 v22, v12
	s_or_b64 exec, exec, s[2:3]
	s_waitcnt lgkmcnt(2)
	v_sub_f32_e32 v12, v4, v26
	v_sub_f32_e32 v13, v5, v25
	v_mul_f32_e32 v4, 0x3fb8aa3b, v4
	v_mul_f32_e32 v5, 0x3fb8aa3b, v5
	v_exp_f32_e32 v4, v4
	v_exp_f32_e32 v5, v5
	v_mul_f32_e32 v12, 0x3fb8aa3b, v12
	v_mul_f32_e32 v13, 0x3fb8aa3b, v13
	v_exp_f32_e32 v12, v12
	v_exp_f32_e32 v13, v13
	v_lshlrev_b32_e32 v16, 16, v0
	v_and_b32_e32 v17, 0xffff0000, v0
	s_mov_b32 s2, 0x3e3504f3
	v_pk_mul_f32 v[16:17], v[16:17], s[2:3] op_sel_hi:[1,0]
	s_movk_i32 s4, 0x300
	v_pk_mul_f32 v[4:5], v[16:17], v[4:5]
	v_pk_mul_f32 v[12:13], v[16:17], v[12:13]
	v_cvt_pk_bf16_f32 v4, v4, v5
	s_waitcnt lgkmcnt(1)
	v_sub_f32_e32 v5, v6, v28
	v_mul_f32_e32 v5, 0x3fb8aa3b, v5
	v_cvt_pk_bf16_f32 v0, v12, v13
	v_exp_f32_e32 v12, v5
	v_sub_f32_e32 v5, v7, v27
	v_mul_f32_e32 v5, 0x3fb8aa3b, v5
	v_exp_f32_e32 v13, v5
	v_mul_f32_e32 v5, 0x3fb8aa3b, v6
	v_exp_f32_e32 v6, v5
	v_mul_f32_e32 v5, 0x3fb8aa3b, v7
	v_exp_f32_e32 v7, v5
	v_lshlrev_b32_e32 v16, 16, v1
	v_and_b32_e32 v17, 0xffff0000, v1
	v_pk_mul_f32 v[16:17], v[16:17], s[2:3] op_sel_hi:[1,0]
	v_or_b32_e32 v31, 2, v24
	v_pk_mul_f32 v[6:7], v[16:17], v[6:7]
	v_pk_mul_f32 v[12:13], v[16:17], v[12:13]
	v_cvt_pk_bf16_f32 v5, v6, v7
	s_waitcnt lgkmcnt(0)
	v_sub_f32_e32 v6, v8, v21
	v_sub_f32_e32 v7, v9, v20
	v_mul_f32_e32 v6, 0x3fb8aa3b, v6
	v_mul_f32_e32 v7, 0x3fb8aa3b, v7
	v_exp_f32_e32 v6, v6
	v_exp_f32_e32 v7, v7
	v_mul_f32_e32 v8, 0x3fb8aa3b, v8
	v_mul_f32_e32 v9, 0x3fb8aa3b, v9
	v_exp_f32_e32 v8, v8
	v_exp_f32_e32 v9, v9
	v_cvt_pk_bf16_f32 v1, v12, v13
	v_lshlrev_b32_e32 v12, 16, v2
	v_and_b32_e32 v13, 0xffff0000, v2
	v_pk_mul_f32 v[12:13], v[12:13], s[2:3] op_sel_hi:[1,0]
	v_lshlrev_b32_e32 v16, 16, v3
	v_pk_mul_f32 v[6:7], v[12:13], v[6:7]
	v_and_b32_e32 v17, 0xffff0000, v3
	v_cvt_pk_bf16_f32 v2, v6, v7
	v_pk_mul_f32 v[6:7], v[12:13], v[8:9]
	ds_read2_b32 v[8:9], v11 offset0:6 offset1:7
	v_cvt_pk_bf16_f32 v6, v6, v7
	v_pk_mul_f32 v[16:17], v[16:17], s[2:3] op_sel_hi:[1,0]
	v_or_b32_e32 v30, 3, v24
	s_waitcnt lgkmcnt(0)
	v_sub_f32_e32 v7, v8, v23
	v_mul_f32_e32 v7, 0x3fb8aa3b, v7
	v_exp_f32_e32 v12, v7
	v_sub_f32_e32 v7, v9, v22
	v_mul_f32_e32 v7, 0x3fb8aa3b, v7
	v_exp_f32_e32 v13, v7
	v_mul_f32_e32 v7, 0x3fb8aa3b, v8
	v_exp_f32_e32 v8, v7
	v_mul_f32_e32 v7, 0x3fb8aa3b, v9
	v_exp_f32_e32 v9, v7
	v_pk_mul_f32 v[12:13], v[16:17], v[12:13]
	v_pk_mul_f32 v[8:9], v[16:17], v[8:9]
	s_nop 0
	v_cvt_pk_bf16_f32 v7, v8, v9
	v_mov_b64_e32 v[8:9], s[68:69]
	v_mad_u64_u32 v[8:9], s[2:3], v100, s4, v[8:9]
	v_cvt_pk_bf16_f32 v3, v12, v13
	v_mov_b32_e32 v12, v9
	v_mad_u64_u32 v[12:13], s[2:3], v101, s4, v[12:13]
	v_mov_b32_e32 v9, v12
	v_lshlrev_b32_e32 v12, 1, v109
	v_mov_b32_e32 v13, v177
	v_lshl_add_u64 v[8:9], v[8:9], 0, v[12:13]
	v_lshlrev_b32_e32 v12, 1, v15
	v_lshl_add_u64 v[8:9], v[8:9], 0, v[12:13]
	s_mov_b32 s2, 0xece4000
	v_add_co_u32_e64 v8, s[38:39], s2, v8
	s_nop 1
	v_addc_co_u32_e64 v9, s[38:39], 0, v9, s[38:39]
	global_store_dwordx4 v[8:9], v[4:7], off offset:512 sc1
	s_nop 1
	v_mad_u32_u24 v4, v107, 33, v15
	v_lshl_add_u32 v29, v4, 2, v105
	ds_read2_b32 v[4:5], v29 offset1:1
	v_add_u32_e32 v6, 0x4400, v29
	ds_read2_b32 v[6:7], v6 offset1:1
	s_waitcnt lgkmcnt(1)
	v_sub_f32_e32 v4, v26, v4
	v_sub_f32_e32 v5, v25, v5
	v_min_f32_e32 v4, 0x42a00000, v4
	v_min_f32_e32 v5, 0x42a00000, v5
	v_mul_f32_e32 v4, 0x3fb8aa3b, v4
	v_mul_f32_e32 v5, 0x3fb8aa3b, v5
	v_exp_f32_e32 v4, v4
	v_exp_f32_e32 v5, v5
	s_waitcnt lgkmcnt(0)
	v_pk_mul_f32 v[4:5], v[6:7], v[4:5]
	ds_read2_b32 v[6:7], v29 offset0:2 offset1:3
	v_cvt_pk_bf16_f32 v4, v4, v5
	v_add_u32_e32 v5, 0x4408, v29
	ds_read2_b32 v[8:9], v5 offset1:1
	s_waitcnt lgkmcnt(1)
	v_sub_f32_e32 v6, v28, v6
	v_sub_f32_e32 v7, v27, v7
	v_min_f32_e32 v6, 0x42a00000, v6
	v_min_f32_e32 v7, 0x42a00000, v7
	v_mul_f32_e32 v6, 0x3fb8aa3b, v6
	v_mul_f32_e32 v7, 0x3fb8aa3b, v7
	v_exp_f32_e32 v6, v6
	v_exp_f32_e32 v7, v7
	s_waitcnt lgkmcnt(0)
	v_pk_mul_f32 v[6:7], v[8:9], v[6:7]
	s_nop 0
	v_cvt_pk_bf16_f32 v5, v6, v7
	ds_read2_b32 v[6:7], v29 offset0:4 offset1:5
	v_add_u32_e32 v8, 0x4410, v29
	ds_read2_b32 v[8:9], v8 offset1:1
	s_waitcnt lgkmcnt(1)
	v_sub_f32_e32 v6, v21, v6
	v_sub_f32_e32 v7, v20, v7
	v_min_f32_e32 v6, 0x42a00000, v6
	v_min_f32_e32 v7, 0x42a00000, v7
	v_mul_f32_e32 v6, 0x3fb8aa3b, v6
	v_mul_f32_e32 v7, 0x3fb8aa3b, v7
	v_exp_f32_e32 v6, v6
	v_exp_f32_e32 v7, v7
	s_waitcnt lgkmcnt(0)
	v_pk_mul_f32 v[6:7], v[8:9], v[6:7]
	ds_read2_b32 v[8:9], v29 offset0:6 offset1:7
	v_cvt_pk_bf16_f32 v6, v6, v7
	v_add_u32_e32 v7, 0x4418, v29
	ds_read2_b32 v[12:13], v7 offset1:1
	s_waitcnt lgkmcnt(1)
	v_sub_f32_e32 v8, v23, v8
	v_sub_f32_e32 v9, v22, v9
	v_min_f32_e32 v8, 0x42a00000, v8
	v_min_f32_e32 v9, 0x42a00000, v9
	v_mul_f32_e32 v8, 0x3fb8aa3b, v8
	v_mul_f32_e32 v9, 0x3fb8aa3b, v9
	v_exp_f32_e32 v8, v8
	v_exp_f32_e32 v9, v9
	s_waitcnt lgkmcnt(0)
	v_pk_mul_f32 v[8:9], v[12:13], v[8:9]
	s_nop 0
	v_cvt_pk_bf16_f32 v7, v8, v9
	v_mov_b32_e32 v8, 0
	s_nop 0
	v_mfma_f32_16x16x32_bf16 v[4:7], v[4:7], v[0:3], 0
	s_and_saveexec_b64 s[2:3], s[36:37]
	v_cmp_gt_u32_e64 s[36:37], v24, v107
	s_nop 5
	v_cndmask_b32_e64 v9, v4, 0, s[36:37]
	v_cmp_lt_u32_e64 s[36:37], v24, v107
	s_nop 1
	v_cndmask_b32_e64 v4, v9, v4, s[36:37]
	v_cndmask_b32_e64 v5, 0, v5, s[36:37]
	v_cmp_le_u32_e64 s[36:37], v31, v107
	s_nop 1
	v_cndmask_b32_e64 v6, 0, v6, s[36:37]
	v_cmp_le_u32_e64 s[36:37], v30, v107
	s_nop 1
	v_cndmask_b32_e64 v7, 0, v7, s[36:37]
	s_or_b64 exec, exec, s[2:3]
	v_mov_b32_e32 v16, 0
	v_mov_b32_e32 v17, 0
	v_mov_b32_e32 v18, 0
	v_mov_b32_e32 v19, 0
	s_and_saveexec_b64 s[4:5], vcc
	s_cbranch_execz .LBB0_222
	v_mad_u32_u24 v9, v10, 33, v15
	v_lshl_add_u32 v9, v9, 2, v105
	ds_read2_b32 v[200:201], v9 offset1:1
	v_add_u32_e32 v253, 0x4400, v9
	ds_read2_b32 v[202:203], v253 offset1:1
	ds_read2_b32 v[204:205], v9 offset0:2 offset1:3
	v_add_u32_e32 v252, 0x4408, v9
	ds_read2_b32 v[220:221], v252 offset1:1
	ds_read2_b32 v[222:223], v9 offset0:4 offset1:5
	v_add_u32_e32 v251, 0x4410, v9
	ds_read2_b32 v[224:225], v251 offset1:1
	ds_read2_b32 v[226:227], v9 offset0:6 offset1:7
	v_add_u32_e32 v250, 0x4418, v9
	ds_read2_b32 v[228:229], v250 offset1:1
	v_cmp_eq_u32_e32 vcc, 1, v108
	s_waitcnt lgkmcnt(1)
	v_sub_f32_e32 v10, v26, v200
	v_sub_f32_e32 v11, v25, v201
	v_min_f32_e32 v10, 0x42a00000, v10
	v_min_f32_e32 v11, 0x42a00000, v11
	v_mul_f32_e32 v10, 0x3fb8aa3b, v10
	v_mul_f32_e32 v11, 0x3fb8aa3b, v11
	v_exp_f32_e32 v10, v10
	v_exp_f32_e32 v11, v11
	s_waitcnt lgkmcnt(0)
	v_pk_mul_f32 v[10:11], v[202:203], v[10:11]
	v_cvt_pk_bf16_f32 v10, v10, v11
	s_waitcnt lgkmcnt(1)
	v_sub_f32_e32 v12, v28, v204
	v_sub_f32_e32 v13, v27, v205
	v_min_f32_e32 v12, 0x42a00000, v12
	v_min_f32_e32 v13, 0x42a00000, v13
	v_mul_f32_e32 v12, 0x3fb8aa3b, v12
	v_mul_f32_e32 v13, 0x3fb8aa3b, v13
	v_exp_f32_e32 v12, v12
	v_exp_f32_e32 v13, v13
	s_waitcnt lgkmcnt(0)
	v_pk_mul_f32 v[12:13], v[220:221], v[12:13]
	s_nop 0
	v_cvt_pk_bf16_f32 v11, v12, v13
	s_waitcnt lgkmcnt(1)
	v_sub_f32_e32 v12, v21, v222
	v_sub_f32_e32 v13, v20, v223
	v_min_f32_e32 v12, 0x42a00000, v12
	v_min_f32_e32 v13, 0x42a00000, v13
	v_mul_f32_e32 v12, 0x3fb8aa3b, v12
	v_mul_f32_e32 v13, 0x3fb8aa3b, v13
	v_exp_f32_e32 v12, v12
	v_exp_f32_e32 v13, v13
	s_waitcnt lgkmcnt(0)
	v_pk_mul_f32 v[12:13], v[224:225], v[12:13]
	v_cvt_pk_bf16_f32 v12, v12, v13
	s_waitcnt lgkmcnt(1)
	v_sub_f32_e32 v9, v23, v226
	v_min_f32_e32 v9, 0x42a00000, v9
	v_mul_f32_e32 v9, 0x3fb8aa3b, v9
	v_exp_f32_e32 v16, v9
	v_sub_f32_e32 v9, v22, v227
	v_min_f32_e32 v9, 0x42a00000, v9
	v_mul_f32_e32 v9, 0x3fb8aa3b, v9
	v_exp_f32_e32 v17, v9
	s_waitcnt lgkmcnt(0)
	v_pk_mul_f32 v[16:17], v[228:229], v[16:17]
	s_nop 0
	v_cvt_pk_bf16_f32 v13, v16, v17
	s_nop 1
	v_mfma_f32_16x16x32_bf16 v[16:19], v[10:13], v[0:3], 0
	s_and_saveexec_b64 s[2:3], vcc
	s_cbranch_execz .LBB0_221
	v_cmp_gt_u32_e32 vcc, v24, v107
	s_nop 4
	v_cndmask_b32_e32 v9, v18, v18, vcc
	v_cndmask_b32_e32 v10, v19, v19, vcc
	v_cndmask_b32_e64 v11, v16, 0, vcc
	v_cmp_lt_u32_e32 vcc, v24, v107
	s_nop 1
	v_cndmask_b32_e32 v16, v11, v16, vcc
	v_cndmask_b32_e32 v10, v10, v19, vcc
	v_cndmask_b32_e32 v9, v9, v18, vcc
	v_cndmask_b32_e32 v17, 0, v17, vcc
	v_cmp_le_u32_e32 vcc, v31, v107
	s_nop 1
	v_cndmask_b32_e32 v18, 0, v9, vcc
	v_cmp_le_u32_e32 vcc, v30, v107
	s_nop 1
	v_cndmask_b32_e32 v19, 0, v10, vcc

.LBB0_222:
	s_or_b64 exec, exec, s[4:5]
	v_cmp_lt_u32_e32 vcc, 1, v108
	v_mov_b32_e32 v9, 0
	v_mov_b32_e32 v10, 0
	v_mov_b32_e32 v11, 0
	s_and_saveexec_b64 s[4:5], vcc
	s_cbranch_execz .LBB0_226
	v_add_u32_e32 v8, 0x1080, v29
	ds_read2_b32 v[200:201], v8 offset1:1
	v_add_u32_e32 v253, 0x5480, v29
	ds_read2_b32 v[202:203], v253 offset1:1
	v_add_u32_e32 v252, 0x1088, v29
	ds_read2_b32 v[204:205], v252 offset1:1
	v_add_u32_e32 v251, 0x5488, v29
	ds_read2_b32 v[220:221], v251 offset1:1
	v_add_u32_e32 v250, 0x1090, v29
	ds_read2_b32 v[222:223], v250 offset1:1
	v_add_u32_e32 v249, 0x5490, v29
	ds_read2_b32 v[224:225], v249 offset1:1
	v_add_u32_e32 v248, 0x1098, v29
	ds_read2_b32 v[226:227], v248 offset1:1
	v_add_u32_e32 v247, 0x5498, v29
	ds_read2_b32 v[228:229], v247 offset1:1
	v_cmp_eq_u32_e64 s[36:37], 2, v108
	s_waitcnt lgkmcnt(1)
	v_sub_f32_e32 v8, v26, v200
	v_sub_f32_e32 v9, v25, v201
	v_min_f32_e32 v8, 0x42a00000, v8
	v_min_f32_e32 v9, 0x42a00000, v9
	v_mul_f32_e32 v8, 0x3fb8aa3b, v8
	v_mul_f32_e32 v9, 0x3fb8aa3b, v9
	v_exp_f32_e32 v8, v8
	v_exp_f32_e32 v9, v9
	s_waitcnt lgkmcnt(0)
	v_pk_mul_f32 v[8:9], v[202:203], v[8:9]
	s_nop 0
	v_cvt_pk_bf16_f32 v8, v8, v9
	s_waitcnt lgkmcnt(0)
	v_sub_f32_e32 v9, v28, v204
	v_min_f32_e32 v9, 0x42a00000, v9
	v_mul_f32_e32 v9, 0x3fb8aa3b, v9
	v_exp_f32_e32 v10, v9
	v_sub_f32_e32 v9, v27, v205
	v_min_f32_e32 v9, 0x42a00000, v9
	v_mul_f32_e32 v9, 0x3fb8aa3b, v9
	v_exp_f32_e32 v11, v9
	s_waitcnt lgkmcnt(0)
	v_pk_mul_f32 v[10:11], v[220:221], v[10:11]
	s_nop 0
	v_cvt_pk_bf16_f32 v9, v10, v11
	s_waitcnt lgkmcnt(1)
	v_sub_f32_e32 v10, v21, v222
	v_sub_f32_e32 v11, v20, v223
	v_min_f32_e32 v10, 0x42a00000, v10
	v_min_f32_e32 v11, 0x42a00000, v11
	v_mul_f32_e32 v10, 0x3fb8aa3b, v10
	v_mul_f32_e32 v11, 0x3fb8aa3b, v11
	v_exp_f32_e32 v10, v10
	v_exp_f32_e32 v11, v11
	s_waitcnt lgkmcnt(0)
	v_pk_mul_f32 v[10:11], v[224:225], v[10:11]
	s_nop 0
	v_cvt_pk_bf16_f32 v10, v10, v11
	s_waitcnt lgkmcnt(0)
	v_sub_f32_e32 v11, v23, v226
	v_min_f32_e32 v11, 0x42a00000, v11
	v_mul_f32_e32 v11, 0x3fb8aa3b, v11
	v_exp_f32_e32 v12, v11
	v_sub_f32_e32 v11, v22, v227
	v_min_f32_e32 v11, 0x42a00000, v11
	v_mul_f32_e32 v11, 0x3fb8aa3b, v11
	v_exp_f32_e32 v13, v11
	s_waitcnt lgkmcnt(0)
	v_pk_mul_f32 v[12:13], v[228:229], v[12:13]
	s_nop 0
	v_cvt_pk_bf16_f32 v11, v12, v13
	s_nop 1
	v_mfma_f32_16x16x32_bf16 v[8:11], v[8:11], v[0:3], 0
	s_waitcnt lgkmcnt(0)
	v_mov_b32_e32 v32, v228
	v_mov_b32_e32 v33, v229
	s_and_saveexec_b64 s[2:3], s[36:37]
	s_cbranch_execz .LBB0_225
	v_cmp_gt_u32_e64 s[36:37], v24, v107
	s_nop 4
	v_cndmask_b32_e64 v12, v10, v10, s[36:37]
	v_cndmask_b32_e64 v13, v11, v11, s[36:37]
	v_cndmask_b32_e64 v14, v8, 0, s[36:37]
	v_cmp_lt_u32_e64 s[36:37], v24, v107
	s_nop 1
	v_cndmask_b32_e64 v8, v14, v8, s[36:37]
	v_cndmask_b32_e64 v11, v13, v11, s[36:37]
	v_cndmask_b32_e64 v10, v12, v10, s[36:37]
	v_cndmask_b32_e64 v9, 0, v9, s[36:37]
	v_cmp_le_u32_e64 s[36:37], v31, v107
	s_nop 1
	v_cndmask_b32_e64 v10, 0, v10, s[36:37]
	v_cmp_le_u32_e64 s[36:37], v30, v107
	s_nop 1
	v_cndmask_b32_e64 v11, 0, v11, s[36:37]

.LBB0_226:
	s_or_b64 exec, exec, s[4:5]
	v_cmp_eq_u32_e64 s[36:37], 3, v108
	v_mov_b32_e32 v12, 0
	v_mov_b32_e32 v13, 0
	v_mov_b32_e32 v14, 0
	v_mov_b32_e32 v32, 0
	s_and_saveexec_b64 s[4:5], s[36:37]
	s_cbranch_execz .LBB0_228
	v_add_u32_e32 v12, 0x18c0, v29
	v_add_u32_e32 v32, 0x18c8, v29
	v_add_u32_e32 v34, 0x5cc8, v29
	v_add_u32_e32 v14, 0x5cc0, v29
	ds_read2_b32 v[200:201], v12 offset1:1
	ds_read2_b32 v[202:203], v32 offset1:1
	ds_read2_b32 v[204:205], v34 offset1:1
	ds_read2_b32 v[220:221], v14 offset1:1
	v_add_u32_e32 v253, 0x18d0, v29
	ds_read2_b32 v[222:223], v253 offset1:1
	v_add_u32_e32 v252, 0x5cd0, v29
	ds_read2_b32 v[224:225], v252 offset1:1
	v_add_u32_e32 v251, 0x18d8, v29
	ds_read2_b32 v[226:227], v251 offset1:1
	v_add_u32_e32 v250, 0x5cd8, v29
	ds_read2_b32 v[228:229], v250 offset1:1
	v_cmp_lt_u32_e64 s[36:37], v24, v107
	s_waitcnt lgkmcnt(2)
	v_sub_f32_e32 v14, v28, v202
	v_min_f32_e32 v14, 0x42a00000, v14
	v_sub_f32_e32 v12, v26, v200
	v_sub_f32_e32 v13, v25, v201
	v_mul_f32_e32 v14, 0x3fb8aa3b, v14
	v_min_f32_e32 v12, 0x42a00000, v12
	v_min_f32_e32 v13, 0x42a00000, v13
	v_exp_f32_e32 v32, v14
	v_sub_f32_e32 v14, v27, v203
	v_mul_f32_e32 v12, 0x3fb8aa3b, v12
	v_mul_f32_e32 v13, 0x3fb8aa3b, v13
	v_min_f32_e32 v14, 0x42a00000, v14
	v_exp_f32_e32 v12, v12
	v_exp_f32_e32 v13, v13
	v_mul_f32_e32 v14, 0x3fb8aa3b, v14
	v_exp_f32_e32 v33, v14
	s_waitcnt lgkmcnt(0)
	v_pk_mul_f32 v[12:13], v[220:221], v[12:13]
	v_cvt_pk_bf16_f32 v26, v12, v13
	v_pk_mul_f32 v[12:13], v[204:205], v[32:33]
	v_cvt_pk_bf16_f32 v27, v12, v13
	s_waitcnt lgkmcnt(3)
	v_sub_f32_e32 v14, v21, v222
	v_min_f32_e32 v14, 0x42a00000, v14
	v_mul_f32_e32 v14, 0x3fb8aa3b, v14
	v_exp_f32_e32 v32, v14
	v_sub_f32_e32 v14, v20, v223
	v_min_f32_e32 v14, 0x42a00000, v14
	v_mul_f32_e32 v14, 0x3fb8aa3b, v14
	v_exp_f32_e32 v33, v14
	s_waitcnt lgkmcnt(1)
	v_sub_f32_e32 v14, v23, v226
	v_min_f32_e32 v14, 0x42a00000, v14
	v_mul_f32_e32 v14, 0x3fb8aa3b, v14
	v_exp_f32_e32 v20, v14
	v_sub_f32_e32 v14, v22, v227
	v_min_f32_e32 v14, 0x42a00000, v14
	v_mul_f32_e32 v14, 0x3fb8aa3b, v14
	v_exp_f32_e32 v21, v14
	v_pk_mul_f32 v[12:13], v[224:225], v[32:33]
	s_nop 0
	v_cvt_pk_bf16_f32 v28, v12, v13
	s_waitcnt lgkmcnt(0)
	v_pk_mul_f32 v[12:13], v[228:229], v[20:21]
	s_nop 0
	v_cvt_pk_bf16_f32 v29, v12, v13
	s_nop 1
	v_mfma_f32_16x16x32_bf16 v[0:3], v[26:29], v[0:3], 0
	s_nop 7
	v_cndmask_b32_e64 v13, 0, v1, s[36:37]
	v_cmp_le_u32_e64 s[36:37], v24, v107
	s_nop 1
	v_cndmask_b32_e64 v12, 0, v0, s[36:37]
	v_cmp_le_u32_e64 s[36:37], v31, v107
	s_nop 1
	v_cndmask_b32_e64 v14, 0, v2, s[36:37]
	v_cmp_le_u32_e64 s[36:37], v30, v107
	s_nop 1
	v_cndmask_b32_e64 v32, 0, v3, s[36:37]
	s_waitcnt lgkmcnt(0)
	v_mov_b32_e32 v34, v226
	v_mov_b32_e32 v35, v227
	v_mov_b32_e32 v36, v228
	v_mov_b32_e32 v37, v229

.LBB0_244:
	s_or_b64 exec, exec, s[2:3]
	s_movk_i32 s2, 0x1040
	v_mad_u32_u24 v23, v27, s2, v28
	v_add_u32_e32 v8, 0xfffffefc, v23
	v_cmp_eq_u32_e64 s[36:37], 0, v27
	v_cmp_ne_u32_e32 vcc, 0, v27
	v_mov_b32_e32 v32, 0
	v_lshl_add_u32 v50, v29, 2, v8
	v_mov_b32_e32 v33, 0
	s_and_saveexec_b64 s[2:3], vcc
	ds_read_b32 v33, v50
	s_or_b64 exec, exec, s[2:3]
	v_lshlrev_b32_e32 v49, 2, v29
	s_and_saveexec_b64 s[2:3], vcc
	s_movk_i32 s4, 0xff00
	v_add3_u32 v8, v23, v49, s4
	ds_read_b32 v32, v8
	s_or_b64 exec, exec, s[2:3]
	v_mul_u32_u24_e32 v8, 0x104, v19
	v_add3_u32 v22, v28, v8, v49
	ds_read2_b32 v[8:9], v22 offset1:1
	v_mov_b32_e32 v36, 0
	v_mov_b32_e32 v38, 0
	s_and_saveexec_b64 s[2:3], vcc
	ds_read_b32 v38, v50 offset:8
	s_or_b64 exec, exec, s[2:3]
	s_and_saveexec_b64 s[2:3], vcc
	s_movk_i32 s4, 0xff08
	v_add3_u32 v10, v23, v49, s4
	ds_read_b32 v36, v10
	s_or_b64 exec, exec, s[2:3]
	ds_read2_b32 v[10:11], v22 offset0:2 offset1:3
	v_mov_b32_e32 v39, 0
	v_mov_b32_e32 v42, 0
	s_and_saveexec_b64 s[2:3], vcc
	ds_read_b32 v42, v50 offset:16
	s_or_b64 exec, exec, s[2:3]
	s_and_saveexec_b64 s[2:3], vcc
	s_movk_i32 s4, 0xff10
	v_add3_u32 v12, v23, v49, s4
	ds_read_b32 v39, v12
	s_or_b64 exec, exec, s[2:3]
	ds_read2_b32 v[12:13], v22 offset0:4 offset1:5
	v_mov_b32_e32 v44, 0
	v_mov_b32_e32 v46, 0
	s_and_saveexec_b64 s[2:3], vcc
	ds_read_b32 v46, v50 offset:24
	s_or_b64 exec, exec, s[2:3]
	s_and_saveexec_b64 s[2:3], vcc
	s_movk_i32 s4, 0xff18
	v_add3_u32 v14, v23, v49, s4
	ds_read_b32 v44, v14
	s_or_b64 exec, exec, s[2:3]
	ds_read2_b32 v[14:15], v22 offset0:6 offset1:7
	v_mov_b32_e32 v34, 0
	v_mov_b32_e32 v35, 0
	s_and_saveexec_b64 s[2:3], vcc
	ds_read_b32 v35, v50 offset:128
	s_or_b64 exec, exec, s[2:3]
	s_and_saveexec_b64 s[2:3], vcc
	s_movk_i32 s4, 0xff80
	v_add3_u32 v16, v23, v49, s4
	ds_read_b32 v34, v16
	s_or_b64 exec, exec, s[2:3]
	ds_read2_b32 v[16:17], v22 offset0:32 offset1:33
	v_mov_b32_e32 v37, 0
	v_mov_b32_e32 v40, 0
	s_and_saveexec_b64 s[2:3], vcc
	ds_read_b32 v40, v50 offset:136
	s_or_b64 exec, exec, s[2:3]
	s_and_saveexec_b64 s[2:3], vcc
	s_movk_i32 s4, 0xff88
	v_add3_u32 v18, v23, v49, s4
	ds_read_b32 v37, v18
	s_or_b64 exec, exec, s[2:3]
	ds_read2_b32 v[18:19], v22 offset0:34 offset1:35
	v_mov_b32_e32 v41, 0
	v_mov_b32_e32 v43, 0
	s_and_saveexec_b64 s[2:3], vcc
	ds_read_b32 v43, v50 offset:144
	s_or_b64 exec, exec, s[2:3]
	s_and_saveexec_b64 s[2:3], vcc
	s_movk_i32 s4, 0xff90
	v_add3_u32 v20, v23, v49, s4
	ds_read_b32 v41, v20
	s_or_b64 exec, exec, s[2:3]
	ds_read2_b32 v[20:21], v22 offset0:36 offset1:37
	v_mov_b32_e32 v45, 0
	v_mov_b32_e32 v47, 0
	s_and_saveexec_b64 s[2:3], vcc
	ds_read_b32 v47, v50 offset:152
	s_or_b64 exec, exec, s[2:3]
	s_and_saveexec_b64 s[2:3], vcc
	s_movk_i32 s4, 0xff98
	v_add3_u32 v23, v23, v49, s4
	ds_read_b32 v45, v23
	s_or_b64 exec, exec, s[2:3]
	s_waitcnt lgkmcnt(2)
	v_sub_f32_e32 v23, v16, v35
	v_mul_f32_e32 v23, 0x3fb8aa3b, v23
	v_exp_f32_e32 v52, v23
	v_sub_f32_e32 v23, v17, v34
	v_mul_f32_e32 v16, 0x3fb8aa3b, v16
	v_mul_f32_e32 v17, 0x3fb8aa3b, v17
	v_exp_f32_e32 v16, v16
	v_exp_f32_e32 v17, v17
	v_mul_f32_e32 v23, 0x3fb8aa3b, v23
	v_exp_f32_e32 v53, v23
	v_lshlrev_b32_e32 v54, 16, v0
	v_and_b32_e32 v55, 0xffff0000, v0
	v_pk_mul_f32 v[16:17], v[16:17], v[54:55]
	v_pk_mul_f32 v[52:53], v[52:53], v[54:55]
	v_cvt_pk_bf16_f32 v16, v16, v17
	s_waitcnt lgkmcnt(1)
	v_sub_f32_e32 v17, v18, v40
	v_mul_f32_e32 v17, 0x3fb8aa3b, v17
	v_cvt_pk_bf16_f32 v0, v52, v53
	v_exp_f32_e32 v52, v17
	v_sub_f32_e32 v17, v19, v37
	v_mul_f32_e32 v17, 0x3fb8aa3b, v17
	v_exp_f32_e32 v53, v17
	v_mul_f32_e32 v17, 0x3fb8aa3b, v18
	v_exp_f32_e32 v18, v17
	v_mul_f32_e32 v17, 0x3fb8aa3b, v19
	v_exp_f32_e32 v19, v17
	v_lshlrev_b32_e32 v54, 16, v1
	v_and_b32_e32 v55, 0xffff0000, v1
	v_pk_mul_f32 v[52:53], v[52:53], v[54:55]
	v_pk_mul_f32 v[18:19], v[18:19], v[54:55]
	v_cvt_pk_bf16_f32 v1, v52, v53
	v_cvt_pk_bf16_f32 v17, v18, v19
	s_waitcnt lgkmcnt(0)
	v_sub_f32_e32 v18, v20, v43
	v_sub_f32_e32 v19, v21, v41
	v_mul_f32_e32 v18, 0x3fb8aa3b, v18
	v_mul_f32_e32 v19, 0x3fb8aa3b, v19
	v_exp_f32_e32 v18, v18
	v_exp_f32_e32 v19, v19
	v_mul_f32_e32 v20, 0x3fb8aa3b, v20
	v_mul_f32_e32 v21, 0x3fb8aa3b, v21
	v_exp_f32_e32 v20, v20
	v_exp_f32_e32 v21, v21
	v_lshlrev_b32_e32 v52, 16, v2
	v_and_b32_e32 v53, 0xffff0000, v2
	v_pk_mul_f32 v[18:19], v[18:19], v[52:53]
	s_movk_i32 s4, 0x300
	v_cvt_pk_bf16_f32 v2, v18, v19
	v_pk_mul_f32 v[18:19], v[20:21], v[52:53]
	v_lshlrev_b32_e32 v52, 16, v4
	v_cvt_pk_bf16_f32 v18, v18, v19
	v_sub_f32_e32 v19, v8, v33
	v_mul_f32_e32 v19, 0x3fb8aa3b, v19
	v_exp_f32_e32 v20, v19
	v_sub_f32_e32 v19, v9, v32
	v_mul_f32_e32 v8, 0x3fb8aa3b, v8
	v_mul_f32_e32 v9, 0x3fb8aa3b, v9
	v_exp_f32_e32 v8, v8
	v_exp_f32_e32 v9, v9
	v_mul_f32_e32 v19, 0x3fb8aa3b, v19
	v_exp_f32_e32 v21, v19
	v_and_b32_e32 v53, 0xffff0000, v4
	v_pk_mul_f32 v[8:9], v[8:9], v[52:53]
	v_or_b32_e32 v50, 2, v30
	v_cvt_pk_bf16_f32 v8, v8, v9
	v_sub_f32_e32 v9, v10, v38
	v_pk_mul_f32 v[20:21], v[20:21], v[52:53]
	v_mul_f32_e32 v9, 0x3fb8aa3b, v9
	v_cvt_pk_bf16_f32 v4, v20, v21
	v_exp_f32_e32 v20, v9
	v_sub_f32_e32 v9, v11, v36
	v_mul_f32_e32 v9, 0x3fb8aa3b, v9
	v_exp_f32_e32 v21, v9
	v_mul_f32_e32 v9, 0x3fb8aa3b, v10
	v_exp_f32_e32 v10, v9
	v_mul_f32_e32 v9, 0x3fb8aa3b, v11
	v_exp_f32_e32 v11, v9
	v_lshlrev_b32_e32 v52, 16, v5
	v_and_b32_e32 v53, 0xffff0000, v5
	v_pk_mul_f32 v[20:21], v[20:21], v[52:53]
	v_pk_mul_f32 v[10:11], v[10:11], v[52:53]
	v_cvt_pk_bf16_f32 v5, v20, v21
	v_cvt_pk_bf16_f32 v9, v10, v11
	v_sub_f32_e32 v10, v12, v42
	v_sub_f32_e32 v11, v13, v39
	v_mul_f32_e32 v10, 0x3fb8aa3b, v10
	v_mul_f32_e32 v11, 0x3fb8aa3b, v11
	v_exp_f32_e32 v10, v10
	v_exp_f32_e32 v11, v11
	v_mul_f32_e32 v12, 0x3fb8aa3b, v12
	v_mul_f32_e32 v13, 0x3fb8aa3b, v13
	v_exp_f32_e32 v12, v12
	v_exp_f32_e32 v13, v13
	v_lshlrev_b32_e32 v20, 16, v6
	v_and_b32_e32 v21, 0xffff0000, v6
	v_pk_mul_f32 v[10:11], v[10:11], v[20:21]
	v_or_b32_e32 v49, 3, v30
	v_cvt_pk_bf16_f32 v6, v10, v11
	v_pk_mul_f32 v[10:11], v[12:13], v[20:21]
	v_lshlrev_b32_e32 v20, 16, v7
	v_cvt_pk_bf16_f32 v10, v10, v11
	v_sub_f32_e32 v11, v14, v46
	v_mul_f32_e32 v11, 0x3fb8aa3b, v11
	v_exp_f32_e32 v12, v11
	v_sub_f32_e32 v11, v15, v44
	v_mul_f32_e32 v11, 0x3fb8aa3b, v11
	v_exp_f32_e32 v13, v11
	v_mul_f32_e32 v11, 0x3fb8aa3b, v14
	v_exp_f32_e32 v14, v11
	v_mul_f32_e32 v11, 0x3fb8aa3b, v15
	v_exp_f32_e32 v15, v11
	v_and_b32_e32 v21, 0xffff0000, v7
	v_pk_mul_f32 v[12:13], v[12:13], v[20:21]
	s_nop 0
	v_cvt_pk_bf16_f32 v7, v12, v13
	v_pk_mul_f32 v[12:13], v[14:15], v[20:21]
	v_lshlrev_b32_e32 v20, 16, v3
	v_cvt_pk_bf16_f32 v11, v12, v13
	ds_read2_b32 v[12:13], v22 offset0:38 offset1:39
	v_and_b32_e32 v21, 0xffff0000, v3
	s_waitcnt lgkmcnt(0)
	v_sub_f32_e32 v14, v12, v47
	v_sub_f32_e32 v15, v13, v45
	v_mul_f32_e32 v12, 0x3fb8aa3b, v12
	v_mul_f32_e32 v13, 0x3fb8aa3b, v13
	v_exp_f32_e32 v12, v12
	v_exp_f32_e32 v13, v13
	v_mul_f32_e32 v14, 0x3fb8aa3b, v14
	v_mul_f32_e32 v15, 0x3fb8aa3b, v15
	v_exp_f32_e32 v14, v14
	v_exp_f32_e32 v15, v15
	v_pk_mul_f32 v[12:13], v[12:13], v[20:21]
	v_pk_mul_f32 v[14:15], v[14:15], v[20:21]
	v_cvt_pk_bf16_f32 v19, v12, v13
	v_mov_b64_e32 v[12:13], s[64:65]
	v_mad_u64_u32 v[12:13], s[2:3], v24, s4, v[12:13]
	v_cvt_pk_bf16_f32 v3, v14, v15
	v_mov_b32_e32 v14, v13
	v_mad_u64_u32 v[14:15], s[2:3], v25, s4, v[14:15]
	v_mov_b32_e32 v13, v14
	v_lshl_add_u64 v[12:13], v[12:13], 0, v[176:177]
	v_lshlrev_b32_e32 v14, 1, v29
	v_mov_b32_e32 v15, v177
	v_lshl_add_u64 v[12:13], v[12:13], 0, v[14:15]
	s_movk_i32 s2, 0x41
	global_store_dwordx4 v[12:13], v[8:11], off sc1
	global_store_dwordx4 v[12:13], v[16:19], off offset:64 sc1
	s_nop 0
	v_mad_u32_u24 v8, v26, s2, v29
	v_lshl_add_u32 v15, v8, 2, v28
	ds_read2_b32 v[8:9], v15 offset1:1
	v_add_u32_e32 v10, 0x4400, v15
	ds_read2_b32 v[10:11], v10 offset1:1
	v_add_u32_e32 v14, 0x4480, v15
	s_waitcnt lgkmcnt(1)
	v_sub_f32_e32 v8, v33, v8
	v_sub_f32_e32 v9, v32, v9
	v_min_f32_e32 v8, 0x42a00000, v8
	v_min_f32_e32 v9, 0x42a00000, v9
	v_mul_f32_e32 v8, 0x3fb8aa3b, v8
	v_mul_f32_e32 v9, 0x3fb8aa3b, v9
	v_exp_f32_e32 v8, v8
	v_exp_f32_e32 v9, v9
	s_waitcnt lgkmcnt(0)
	v_pk_mul_f32 v[8:9], v[10:11], v[8:9]
	ds_read2_b32 v[10:11], v15 offset0:2 offset1:3
	v_cvt_pk_bf16_f32 v8, v8, v9
	v_add_u32_e32 v9, 0x4408, v15
	ds_read2_b32 v[12:13], v9 offset1:1
	s_waitcnt lgkmcnt(1)
	v_sub_f32_e32 v10, v38, v10
	v_sub_f32_e32 v11, v36, v11
	v_min_f32_e32 v10, 0x42a00000, v10
	v_min_f32_e32 v11, 0x42a00000, v11
	v_mul_f32_e32 v10, 0x3fb8aa3b, v10
	v_mul_f32_e32 v11, 0x3fb8aa3b, v11
	v_exp_f32_e32 v10, v10
	v_exp_f32_e32 v11, v11
	s_waitcnt lgkmcnt(0)
	v_pk_mul_f32 v[10:11], v[12:13], v[10:11]
	s_nop 0
	v_cvt_pk_bf16_f32 v9, v10, v11
	ds_read2_b32 v[10:11], v15 offset0:4 offset1:5
	v_add_u32_e32 v12, 0x4410, v15
	ds_read2_b32 v[12:13], v12 offset1:1
	s_waitcnt lgkmcnt(1)
	v_sub_f32_e32 v10, v42, v10
	v_sub_f32_e32 v11, v39, v11
	v_min_f32_e32 v10, 0x42a00000, v10
	v_min_f32_e32 v11, 0x42a00000, v11
	v_mul_f32_e32 v10, 0x3fb8aa3b, v10
	v_mul_f32_e32 v11, 0x3fb8aa3b, v11
	v_exp_f32_e32 v10, v10
	v_exp_f32_e32 v11, v11
	s_waitcnt lgkmcnt(0)
	v_pk_mul_f32 v[10:11], v[12:13], v[10:11]
	ds_read2_b32 v[12:13], v15 offset0:6 offset1:7
	v_cvt_pk_bf16_f32 v10, v10, v11
	v_add_u32_e32 v11, 0x4418, v15
	ds_read2_b32 v[16:17], v11 offset1:1
	s_waitcnt lgkmcnt(1)
	v_sub_f32_e32 v12, v46, v12
	v_sub_f32_e32 v13, v44, v13
	v_min_f32_e32 v12, 0x42a00000, v12
	v_min_f32_e32 v13, 0x42a00000, v13
	v_mul_f32_e32 v12, 0x3fb8aa3b, v12
	v_mul_f32_e32 v13, 0x3fb8aa3b, v13
	v_exp_f32_e32 v12, v12
	v_exp_f32_e32 v13, v13
	s_waitcnt lgkmcnt(0)
	v_pk_mul_f32 v[12:13], v[16:17], v[12:13]
	s_nop 0
	v_cvt_pk_bf16_f32 v11, v12, v13
	ds_read2_b32 v[12:13], v15 offset0:32 offset1:33
	ds_read2_b32 v[16:17], v14 offset1:1
	v_mfma_f32_16x16x32_bf16 v[8:11], v[8:11], v[4:7], 0
	s_waitcnt lgkmcnt(1)
	v_sub_f32_e32 v12, v35, v12
	v_sub_f32_e32 v13, v34, v13
	v_min_f32_e32 v12, 0x42a00000, v12
	v_min_f32_e32 v13, 0x42a00000, v13
	v_mul_f32_e32 v12, 0x3fb8aa3b, v12
	v_mul_f32_e32 v13, 0x3fb8aa3b, v13
	v_exp_f32_e32 v12, v12
	v_exp_f32_e32 v13, v13
	s_waitcnt lgkmcnt(0)
	v_pk_mul_f32 v[12:13], v[16:17], v[12:13]
	ds_read2_b32 v[16:17], v15 offset0:34 offset1:35
	v_cvt_pk_bf16_f32 v12, v12, v13
	v_add_u32_e32 v13, 0x4488, v15
	ds_read2_b32 v[18:19], v13 offset1:1
	s_waitcnt lgkmcnt(1)
	v_sub_f32_e32 v14, v40, v16
	v_min_f32_e32 v14, 0x42a00000, v14
	v_mul_f32_e32 v14, 0x3fb8aa3b, v14
	v_exp_f32_e32 v16, v14
	v_sub_f32_e32 v14, v37, v17
	v_min_f32_e32 v14, 0x42a00000, v14
	v_mul_f32_e32 v14, 0x3fb8aa3b, v14
	v_exp_f32_e32 v17, v14
	v_add_u32_e32 v14, 0x4490, v15
	s_waitcnt lgkmcnt(0)
	v_pk_mul_f32 v[16:17], v[18:19], v[16:17]
	s_nop 0
	v_cvt_pk_bf16_f32 v13, v16, v17
	ds_read2_b32 v[16:17], v15 offset0:36 offset1:37
	ds_read2_b32 v[18:19], v14 offset1:1
	s_waitcnt lgkmcnt(1)
	v_sub_f32_e32 v16, v43, v16
	v_sub_f32_e32 v17, v41, v17
	v_min_f32_e32 v16, 0x42a00000, v16
	v_min_f32_e32 v17, 0x42a00000, v17
	v_mul_f32_e32 v16, 0x3fb8aa3b, v16
	v_mul_f32_e32 v17, 0x3fb8aa3b, v17
	v_exp_f32_e32 v16, v16
	v_exp_f32_e32 v17, v17
	s_waitcnt lgkmcnt(0)
	v_pk_mul_f32 v[16:17], v[18:19], v[16:17]
	s_nop 0
	v_cvt_pk_bf16_f32 v14, v16, v17
	ds_read2_b32 v[16:17], v15 offset0:38 offset1:39
	v_add_u32_e32 v18, 0x4498, v15
	ds_read2_b32 v[18:19], v18 offset1:1
	s_waitcnt lgkmcnt(1)
	v_sub_f32_e32 v15, v47, v16
	v_min_f32_e32 v15, 0x42a00000, v15
	v_mul_f32_e32 v15, 0x3fb8aa3b, v15
	v_exp_f32_e32 v16, v15
	v_sub_f32_e32 v15, v45, v17
	v_min_f32_e32 v15, 0x42a00000, v15
	v_mul_f32_e32 v15, 0x3fb8aa3b, v15
	v_exp_f32_e32 v17, v15
	s_waitcnt lgkmcnt(0)
	v_pk_mul_f32 v[16:17], v[18:19], v[16:17]
	s_nop 0
	v_cvt_pk_bf16_f32 v15, v16, v17
	v_mov_b32_e32 v16, 0
	s_nop 0
	v_mfma_f32_16x16x32_bf16 v[8:11], v[12:15], v[0:3], v[8:11]
	s_and_saveexec_b64 s[2:3], s[36:37]
	v_cmp_gt_u32_e64 s[36:37], v30, v26
	s_nop 5
	v_cndmask_b32_e64 v12, v8, 0, s[36:37]
	v_cmp_lt_u32_e64 s[36:37], v30, v26
	s_nop 1
	v_cndmask_b32_e64 v8, v12, v8, s[36:37]
	v_cndmask_b32_e64 v9, 0, v9, s[36:37]
	v_cmp_le_u32_e64 s[36:37], v50, v26
	s_nop 1
	v_cndmask_b32_e64 v10, 0, v10, s[36:37]
	v_cmp_le_u32_e64 s[36:37], v49, v26
	s_nop 1
	v_cndmask_b32_e64 v11, 0, v11, s[36:37]
	s_or_b64 exec, exec, s[2:3]
	v_mov_b32_e32 v20, 0
	v_mov_b32_e32 v21, 0
	v_mov_b32_e32 v22, 0
	v_mov_b32_e32 v23, 0
	s_and_saveexec_b64 s[4:5], vcc
	s_cbranch_execz .LBB0_282
	s_movk_i32 s2, 0x41
	v_mad_u32_u24 v12, v51, s2, v29
	v_lshl_add_u32 v17, v12, 2, v28
	ds_read2_b32 v[80:81], v17 offset1:1
	v_add_u32_e32 v175, 0x4400, v17
	ds_read2_b32 v[82:83], v175 offset1:1
	ds_read2_b32 v[84:85], v17 offset0:2 offset1:3
	v_add_u32_e32 v174, 0x4408, v17
	ds_read2_b32 v[86:87], v174 offset1:1
	ds_read2_b32 v[88:89], v17 offset0:4 offset1:5
	v_add_u32_e32 v173, 0x4410, v17
	ds_read2_b32 v[90:91], v173 offset1:1
	ds_read2_b32 v[92:93], v17 offset0:6 offset1:7
	v_add_u32_e32 v172, 0x4418, v17
	ds_read2_b32 v[94:95], v172 offset1:1
	ds_read2_b32 v[96:97], v17 offset0:32 offset1:33
	v_add_u32_e32 v171, 0x4480, v17
	ds_read2_b32 v[98:99], v171 offset1:1
	ds_read2_b32 v[100:101], v17 offset0:34 offset1:35
	v_add_u32_e32 v170, 0x4488, v17
	ds_read2_b32 v[102:103], v170 offset1:1
	ds_read2_b32 v[104:105], v17 offset0:36 offset1:37
	v_add_u32_e32 v169, 0x4490, v17
	ds_read2_b32 v[106:107], v169 offset1:1
	ds_read2_b32 v[108:109], v17 offset0:38 offset1:39
	v_add_u32_e32 v168, 0x4498, v17
	ds_read2_b32 v[110:111], v168 offset1:1
	v_cmp_eq_u32_e32 vcc, 1, v27
	s_waitcnt lgkmcnt(1)
	v_sub_f32_e32 v12, v33, v80
	v_sub_f32_e32 v13, v32, v81
	v_min_f32_e32 v12, 0x42a00000, v12
	v_min_f32_e32 v13, 0x42a00000, v13
	v_mul_f32_e32 v12, 0x3fb8aa3b, v12
	v_mul_f32_e32 v13, 0x3fb8aa3b, v13
	v_exp_f32_e32 v12, v12
	v_exp_f32_e32 v13, v13
	s_waitcnt lgkmcnt(0)
	v_pk_mul_f32 v[12:13], v[82:83], v[12:13]
	v_cvt_pk_bf16_f32 v12, v12, v13
	s_waitcnt lgkmcnt(1)
	v_sub_f32_e32 v14, v38, v84
	v_sub_f32_e32 v15, v36, v85
	v_min_f32_e32 v14, 0x42a00000, v14
	v_min_f32_e32 v15, 0x42a00000, v15
	v_mul_f32_e32 v14, 0x3fb8aa3b, v14
	v_mul_f32_e32 v15, 0x3fb8aa3b, v15
	v_exp_f32_e32 v14, v14
	v_exp_f32_e32 v15, v15
	s_waitcnt lgkmcnt(0)
	v_pk_mul_f32 v[14:15], v[86:87], v[14:15]
	s_nop 0
	v_cvt_pk_bf16_f32 v13, v14, v15
	s_waitcnt lgkmcnt(1)
	v_sub_f32_e32 v14, v42, v88
	v_sub_f32_e32 v15, v39, v89
	v_min_f32_e32 v14, 0x42a00000, v14
	v_min_f32_e32 v15, 0x42a00000, v15
	v_mul_f32_e32 v14, 0x3fb8aa3b, v14
	v_mul_f32_e32 v15, 0x3fb8aa3b, v15
	v_exp_f32_e32 v14, v14
	v_exp_f32_e32 v15, v15
	s_waitcnt lgkmcnt(0)
	v_pk_mul_f32 v[14:15], v[90:91], v[14:15]
	v_cvt_pk_bf16_f32 v14, v14, v15
	s_waitcnt lgkmcnt(1)
	v_sub_f32_e32 v18, v46, v92
	v_sub_f32_e32 v19, v44, v93
	v_min_f32_e32 v18, 0x42a00000, v18
	v_min_f32_e32 v19, 0x42a00000, v19
	v_mul_f32_e32 v18, 0x3fb8aa3b, v18
	v_mul_f32_e32 v19, 0x3fb8aa3b, v19
	v_exp_f32_e32 v18, v18
	v_exp_f32_e32 v19, v19
	s_waitcnt lgkmcnt(0)
	v_pk_mul_f32 v[18:19], v[94:95], v[18:19]
	s_nop 0
	v_cvt_pk_bf16_f32 v15, v18, v19
	s_nop 1
	v_mfma_f32_16x16x32_bf16 v[12:15], v[12:15], v[4:7], 0
	s_waitcnt lgkmcnt(1)
	v_sub_f32_e32 v18, v35, v96
	v_sub_f32_e32 v19, v34, v97
	v_min_f32_e32 v18, 0x42a00000, v18
	v_min_f32_e32 v19, 0x42a00000, v19
	v_mul_f32_e32 v18, 0x3fb8aa3b, v18
	v_mul_f32_e32 v19, 0x3fb8aa3b, v19
	v_exp_f32_e32 v18, v18
	v_exp_f32_e32 v19, v19
	s_waitcnt lgkmcnt(0)
	v_pk_mul_f32 v[18:19], v[98:99], v[18:19]
	v_cvt_pk_bf16_f32 v18, v18, v19
	s_waitcnt lgkmcnt(1)
	v_sub_f32_e32 v20, v40, v100
	v_sub_f32_e32 v21, v37, v101
	v_min_f32_e32 v20, 0x42a00000, v20
	v_min_f32_e32 v21, 0x42a00000, v21
	v_mul_f32_e32 v20, 0x3fb8aa3b, v20
	v_mul_f32_e32 v21, 0x3fb8aa3b, v21
	v_exp_f32_e32 v20, v20
	v_exp_f32_e32 v21, v21
	s_waitcnt lgkmcnt(0)
	v_pk_mul_f32 v[20:21], v[102:103], v[20:21]
	s_nop 0
	v_cvt_pk_bf16_f32 v19, v20, v21
	s_waitcnt lgkmcnt(1)
	v_sub_f32_e32 v20, v43, v104
	v_sub_f32_e32 v21, v41, v105
	v_min_f32_e32 v20, 0x42a00000, v20
	v_min_f32_e32 v21, 0x42a00000, v21
	v_mul_f32_e32 v20, 0x3fb8aa3b, v20
	v_mul_f32_e32 v21, 0x3fb8aa3b, v21
	v_exp_f32_e32 v20, v20
	v_exp_f32_e32 v21, v21
	s_waitcnt lgkmcnt(0)
	v_pk_mul_f32 v[20:21], v[106:107], v[20:21]
	v_cvt_pk_bf16_f32 v20, v20, v21
	s_waitcnt lgkmcnt(1)
	v_sub_f32_e32 v17, v47, v108
	v_min_f32_e32 v17, 0x42a00000, v17
	v_mul_f32_e32 v17, 0x3fb8aa3b, v17
	v_exp_f32_e32 v22, v17
	v_sub_f32_e32 v17, v45, v109
	v_min_f32_e32 v17, 0x42a00000, v17
	v_mul_f32_e32 v17, 0x3fb8aa3b, v17
	v_exp_f32_e32 v23, v17
	s_waitcnt lgkmcnt(0)
	v_pk_mul_f32 v[22:23], v[110:111], v[22:23]
	s_nop 0
	v_cvt_pk_bf16_f32 v21, v22, v23
	s_nop 1
	v_mfma_f32_16x16x32_bf16 v[20:23], v[18:21], v[0:3], v[12:15]
	s_waitcnt lgkmcnt(0)
	v_mov_b32_e32 v52, v110
	v_mov_b32_e32 v53, v111
	s_and_saveexec_b64 s[2:3], vcc
	v_cmp_gt_u32_e32 vcc, v30, v26
	s_nop 5
	v_cndmask_b32_e64 v12, v20, 0, vcc
	v_cmp_lt_u32_e32 vcc, v30, v26
	s_nop 1
	v_cndmask_b32_e32 v20, v12, v20, vcc
	v_cndmask_b32_e32 v21, 0, v21, vcc
	v_cmp_le_u32_e32 vcc, v50, v26
	s_nop 1
	v_cndmask_b32_e32 v22, 0, v22, vcc
	v_cmp_le_u32_e32 vcc, v49, v26
	s_nop 1
	v_cndmask_b32_e32 v23, 0, v23, vcc
	s_or_b64 exec, exec, s[2:3]
.LBB0_282:
	s_or_b64 exec, exec, s[4:5]
	v_cmp_lt_u32_e32 vcc, 1, v27
	v_mov_b32_e32 v17, 0
	v_mov_b32_e32 v18, 0
	v_mov_b32_e32 v19, 0
	s_and_saveexec_b64 s[4:5], vcc
	s_cbranch_execz .LBB0_286
	s_movk_i32 s2, 0x41
	v_mad_u32_u24 v12, v48, s2, v29
	v_lshl_add_u32 v19, v12, 2, v28
	ds_read2_b32 v[80:81], v19 offset1:1
	v_add_u32_e32 v175, 0x4400, v19
	ds_read2_b32 v[82:83], v175 offset1:1
	ds_read2_b32 v[84:85], v19 offset0:2 offset1:3
	v_add_u32_e32 v174, 0x4408, v19
	ds_read2_b32 v[86:87], v174 offset1:1
	ds_read2_b32 v[88:89], v19 offset0:4 offset1:5
	v_add_u32_e32 v173, 0x4410, v19
	ds_read2_b32 v[90:91], v173 offset1:1
	ds_read2_b32 v[92:93], v19 offset0:6 offset1:7
	v_add_u32_e32 v172, 0x4418, v19
	ds_read2_b32 v[94:95], v172 offset1:1
	ds_read2_b32 v[96:97], v19 offset0:32 offset1:33
	v_add_u32_e32 v171, 0x4480, v19
	ds_read2_b32 v[98:99], v171 offset1:1
	ds_read2_b32 v[100:101], v19 offset0:34 offset1:35
	v_add_u32_e32 v170, 0x4488, v19
	ds_read2_b32 v[102:103], v170 offset1:1
	ds_read2_b32 v[104:105], v19 offset0:36 offset1:37
	v_add_u32_e32 v169, 0x4490, v19
	ds_read2_b32 v[106:107], v169 offset1:1
	ds_read2_b32 v[108:109], v19 offset0:38 offset1:39
	v_add_u32_e32 v168, 0x4498, v19
	ds_read2_b32 v[110:111], v168 offset1:1
	v_cmp_eq_u32_e64 s[36:37], 2, v27
	s_waitcnt lgkmcnt(1)
	v_sub_f32_e32 v12, v33, v80
	v_sub_f32_e32 v13, v32, v81
	v_min_f32_e32 v12, 0x42a00000, v12
	v_min_f32_e32 v13, 0x42a00000, v13
	v_mul_f32_e32 v12, 0x3fb8aa3b, v12
	v_mul_f32_e32 v13, 0x3fb8aa3b, v13
	v_exp_f32_e32 v12, v12
	v_exp_f32_e32 v13, v13
	s_waitcnt lgkmcnt(0)
	v_pk_mul_f32 v[12:13], v[82:83], v[12:13]
	v_cvt_pk_bf16_f32 v12, v12, v13
	s_waitcnt lgkmcnt(1)
	v_sub_f32_e32 v14, v38, v84
	v_sub_f32_e32 v15, v36, v85
	v_min_f32_e32 v14, 0x42a00000, v14
	v_min_f32_e32 v15, 0x42a00000, v15
	v_mul_f32_e32 v14, 0x3fb8aa3b, v14
	v_mul_f32_e32 v15, 0x3fb8aa3b, v15
	v_exp_f32_e32 v14, v14
	v_exp_f32_e32 v15, v15
	s_waitcnt lgkmcnt(0)
	v_pk_mul_f32 v[14:15], v[86:87], v[14:15]
	s_nop 0
	v_cvt_pk_bf16_f32 v13, v14, v15
	s_waitcnt lgkmcnt(1)
	v_sub_f32_e32 v14, v42, v88
	v_sub_f32_e32 v15, v39, v89
	v_min_f32_e32 v14, 0x42a00000, v14
	v_min_f32_e32 v15, 0x42a00000, v15
	v_mul_f32_e32 v14, 0x3fb8aa3b, v14
	v_mul_f32_e32 v15, 0x3fb8aa3b, v15
	v_exp_f32_e32 v14, v14
	v_exp_f32_e32 v15, v15
	s_waitcnt lgkmcnt(0)
	v_pk_mul_f32 v[14:15], v[90:91], v[14:15]
	v_cvt_pk_bf16_f32 v14, v14, v15
	s_waitcnt lgkmcnt(1)
	v_sub_f32_e32 v16, v46, v92
	v_sub_f32_e32 v17, v44, v93
	v_min_f32_e32 v16, 0x42a00000, v16
	v_min_f32_e32 v17, 0x42a00000, v17
	v_mul_f32_e32 v16, 0x3fb8aa3b, v16
	v_mul_f32_e32 v17, 0x3fb8aa3b, v17
	v_exp_f32_e32 v16, v16
	v_exp_f32_e32 v17, v17
	s_waitcnt lgkmcnt(0)
	v_pk_mul_f32 v[16:17], v[94:95], v[16:17]
	s_nop 0
	v_cvt_pk_bf16_f32 v15, v16, v17
	s_nop 1
	v_mfma_f32_16x16x32_bf16 v[12:15], v[12:15], v[4:7], 0
	s_waitcnt lgkmcnt(1)
	v_sub_f32_e32 v16, v35, v96
	v_sub_f32_e32 v17, v34, v97
	v_min_f32_e32 v16, 0x42a00000, v16
	v_min_f32_e32 v17, 0x42a00000, v17
	v_mul_f32_e32 v16, 0x3fb8aa3b, v16
	v_mul_f32_e32 v17, 0x3fb8aa3b, v17
	v_exp_f32_e32 v16, v16
	v_exp_f32_e32 v17, v17
	s_waitcnt lgkmcnt(0)
	v_pk_mul_f32 v[16:17], v[98:99], v[16:17]
	v_cvt_pk_bf16_f32 v16, v16, v17
	s_waitcnt lgkmcnt(1)
	v_sub_f32_e32 v18, v40, v100
	v_min_f32_e32 v18, 0x42a00000, v18
	v_mul_f32_e32 v18, 0x3fb8aa3b, v18
	v_exp_f32_e32 v52, v18
	v_sub_f32_e32 v18, v37, v101
	v_min_f32_e32 v18, 0x42a00000, v18
	v_mul_f32_e32 v18, 0x3fb8aa3b, v18
	v_exp_f32_e32 v53, v18
	s_waitcnt lgkmcnt(0)
	v_pk_mul_f32 v[52:53], v[102:103], v[52:53]
	s_nop 0
	v_cvt_pk_bf16_f32 v17, v52, v53
	s_waitcnt lgkmcnt(1)
	v_sub_f32_e32 v48, v43, v104
	v_min_f32_e32 v48, 0x42a00000, v48
	v_mul_f32_e32 v48, 0x3fb8aa3b, v48
	v_exp_f32_e32 v52, v48
	v_sub_f32_e32 v48, v41, v105
	v_min_f32_e32 v48, 0x42a00000, v48
	v_mul_f32_e32 v48, 0x3fb8aa3b, v48
	v_exp_f32_e32 v53, v48
	s_waitcnt lgkmcnt(0)
	v_pk_mul_f32 v[52:53], v[106:107], v[52:53]
	s_nop 0
	v_cvt_pk_bf16_f32 v18, v52, v53
	s_waitcnt lgkmcnt(1)
	v_sub_f32_e32 v19, v47, v108
	v_min_f32_e32 v19, 0x42a00000, v19
	v_mul_f32_e32 v19, 0x3fb8aa3b, v19
	v_exp_f32_e32 v52, v19
	v_sub_f32_e32 v19, v45, v109
	v_min_f32_e32 v19, 0x42a00000, v19
	v_mul_f32_e32 v19, 0x3fb8aa3b, v19
	v_exp_f32_e32 v53, v19
	s_waitcnt lgkmcnt(0)
	v_pk_mul_f32 v[52:53], v[110:111], v[52:53]
	s_nop 0
	v_cvt_pk_bf16_f32 v19, v52, v53
	s_nop 1
	v_mfma_f32_16x16x32_bf16 v[16:19], v[16:19], v[0:3], v[12:15]
	s_waitcnt lgkmcnt(0)
	v_mov_b32_e32 v54, v110
	v_mov_b32_e32 v55, v111
	s_and_saveexec_b64 s[2:3], s[36:37]
	v_cmp_gt_u32_e64 s[36:37], v30, v26
	s_nop 5
	v_cndmask_b32_e64 v12, v16, 0, s[36:37]
	v_cmp_lt_u32_e64 s[36:37], v30, v26
	s_nop 1
	v_cndmask_b32_e64 v16, v12, v16, s[36:37]
	v_cndmask_b32_e64 v17, 0, v17, s[36:37]
	v_cmp_le_u32_e64 s[36:37], v50, v26
	s_nop 1
	v_cndmask_b32_e64 v18, 0, v18, s[36:37]
	v_cmp_le_u32_e64 s[36:37], v49, v26
	s_nop 1
	v_cndmask_b32_e64 v19, 0, v19, s[36:37]
	s_or_b64 exec, exec, s[2:3]
.LBB0_286:
	s_or_b64 exec, exec, s[4:5]
	v_cmp_eq_u32_e64 s[36:37], 3, v27
	v_mov_b32_e32 v12, 0
	v_mov_b32_e32 v13, 0
	v_mov_b32_e32 v14, 0
	v_mov_b32_e32 v15, 0
	s_and_saveexec_b64 s[2:3], s[36:37]
	s_cbranch_execz .LBB0_288
	s_movk_i32 s4, 0x41
	v_mad_u32_u24 v12, v31, s4, v29
	v_lshl_add_u32 v27, v12, 2, v28
	ds_read2_b32 v[80:81], v27 offset1:1
	ds_read2_b32 v[82:83], v27 offset0:2 offset1:3
	ds_read2_b32 v[84:85], v27 offset0:4 offset1:5
	ds_read2_b32 v[86:87], v27 offset0:6 offset1:7
	v_add_u32_e32 v175, 0x4400, v27
	ds_read2_b32 v[88:89], v175 offset1:1
	v_add_u32_e32 v174, 0x4408, v27
	ds_read2_b32 v[90:91], v174 offset1:1
	v_add_u32_e32 v173, 0x4410, v27
	ds_read2_b32 v[92:93], v173 offset1:1
	v_add_u32_e32 v172, 0x4418, v27
	ds_read2_b32 v[94:95], v172 offset1:1
	ds_read2_b32 v[96:97], v27 offset0:32 offset1:33
	ds_read2_b32 v[98:99], v27 offset0:34 offset1:35
	ds_read2_b32 v[100:101], v27 offset0:36 offset1:37
	ds_read2_b32 v[102:103], v27 offset0:38 offset1:39
	v_add_u32_e32 v171, 0x4480, v27
	ds_read2_b32 v[104:105], v171 offset1:1
	v_add_u32_e32 v170, 0x4488, v27
	ds_read2_b32 v[106:107], v170 offset1:1
	v_add_u32_e32 v169, 0x4490, v27
	ds_read2_b32 v[108:109], v169 offset1:1
	v_add_u32_e32 v168, 0x4498, v27
	ds_read2_b32 v[110:111], v168 offset1:1
	v_cmp_lt_u32_e64 s[36:37], v30, v26
	s_waitcnt lgkmcnt(2)
	v_sub_f32_e32 v14, v38, v82
	v_sub_f32_e32 v12, v33, v80
	v_sub_f32_e32 v13, v32, v81
	v_min_f32_e32 v12, 0x42a00000, v12
	v_min_f32_e32 v13, 0x42a00000, v13
	v_mul_f32_e32 v12, 0x3fb8aa3b, v12
	v_mul_f32_e32 v13, 0x3fb8aa3b, v13
	v_exp_f32_e32 v12, v12
	v_exp_f32_e32 v13, v13
	v_sub_f32_e32 v15, v36, v83
	s_waitcnt lgkmcnt(0)
	v_pk_mul_f32 v[12:13], v[88:89], v[12:13]
	v_min_f32_e32 v14, 0x42a00000, v14
	v_cvt_pk_bf16_f32 v12, v12, v13
	v_sub_f32_e32 v13, v42, v84
	v_min_f32_e32 v13, 0x42a00000, v13
	v_mul_f32_e32 v13, 0x3fb8aa3b, v13
	v_exp_f32_e32 v32, v13
	v_sub_f32_e32 v13, v39, v85
	v_min_f32_e32 v13, 0x42a00000, v13
	v_mul_f32_e32 v13, 0x3fb8aa3b, v13
	v_exp_f32_e32 v33, v13
	v_sub_f32_e32 v13, v46, v86
	v_min_f32_e32 v13, 0x42a00000, v13
	v_mul_f32_e32 v13, 0x3fb8aa3b, v13
	v_min_f32_e32 v15, 0x42a00000, v15
	v_exp_f32_e32 v38, v13
	v_sub_f32_e32 v13, v44, v87
	v_mul_f32_e32 v14, 0x3fb8aa3b, v14
	v_mul_f32_e32 v15, 0x3fb8aa3b, v15
	v_min_f32_e32 v13, 0x42a00000, v13
	v_exp_f32_e32 v14, v14
	v_exp_f32_e32 v15, v15
	v_mul_f32_e32 v13, 0x3fb8aa3b, v13
	v_exp_f32_e32 v39, v13
	s_waitcnt lgkmcnt(2)
	v_pk_mul_f32 v[14:15], v[90:91], v[14:15]
	s_nop 0
	v_cvt_pk_bf16_f32 v13, v14, v15
	s_waitcnt lgkmcnt(1)
	v_pk_mul_f32 v[14:15], v[92:93], v[32:33]
	s_waitcnt lgkmcnt(0)
	v_pk_mul_f32 v[32:33], v[94:95], v[38:39]
	v_cvt_pk_bf16_f32 v14, v14, v15
	v_cvt_pk_bf16_f32 v15, v32, v33
	s_nop 1
	v_mfma_f32_16x16x32_bf16 v[4:7], v[12:15], v[4:7], 0
	s_waitcnt lgkmcnt(2)
	v_sub_f32_e32 v14, v40, v98
	v_sub_f32_e32 v12, v35, v96
	v_sub_f32_e32 v13, v34, v97
	v_min_f32_e32 v12, 0x42a00000, v12
	v_min_f32_e32 v13, 0x42a00000, v13
	v_mul_f32_e32 v12, 0x3fb8aa3b, v12
	v_mul_f32_e32 v13, 0x3fb8aa3b, v13
	v_exp_f32_e32 v12, v12
	v_exp_f32_e32 v13, v13
	v_sub_f32_e32 v15, v37, v99
	v_min_f32_e32 v14, 0x42a00000, v14
	v_min_f32_e32 v15, 0x42a00000, v15
	s_waitcnt lgkmcnt(0)
	v_pk_mul_f32 v[12:13], v[104:105], v[12:13]
	v_cvt_pk_bf16_f32 v12, v12, v13
	v_sub_f32_e32 v13, v43, v100
	v_min_f32_e32 v13, 0x42a00000, v13
	v_mul_f32_e32 v13, 0x3fb8aa3b, v13
	v_exp_f32_e32 v32, v13
	v_sub_f32_e32 v13, v41, v101
	v_min_f32_e32 v13, 0x42a00000, v13
	v_mul_f32_e32 v13, 0x3fb8aa3b, v13
	v_exp_f32_e32 v33, v13
	v_sub_f32_e32 v13, v47, v102
	v_min_f32_e32 v13, 0x42a00000, v13
	v_mul_f32_e32 v13, 0x3fb8aa3b, v13
	v_exp_f32_e32 v34, v13
	v_sub_f32_e32 v13, v45, v103
	v_mul_f32_e32 v14, 0x3fb8aa3b, v14
	v_mul_f32_e32 v15, 0x3fb8aa3b, v15
	v_min_f32_e32 v13, 0x42a00000, v13
	v_exp_f32_e32 v14, v14
	v_exp_f32_e32 v15, v15
	v_mul_f32_e32 v13, 0x3fb8aa3b, v13
	v_exp_f32_e32 v35, v13
	s_waitcnt lgkmcnt(2)
	v_pk_mul_f32 v[14:15], v[106:107], v[14:15]
	s_nop 0
	v_cvt_pk_bf16_f32 v13, v14, v15
	s_waitcnt lgkmcnt(1)
	v_pk_mul_f32 v[14:15], v[108:109], v[32:33]
	s_waitcnt lgkmcnt(0)
	v_pk_mul_f32 v[32:33], v[110:111], v[34:35]
	v_cvt_pk_bf16_f32 v14, v14, v15
	v_cvt_pk_bf16_f32 v15, v32, v33
	s_nop 1
	v_mfma_f32_16x16x32_bf16 v[0:3], v[12:15], v[0:3], v[4:7]
	s_nop 7
	v_cndmask_b32_e64 v13, 0, v1, s[36:37]
	v_cmp_le_u32_e64 s[36:37], v30, v26
	s_nop 1
	v_cndmask_b32_e64 v12, 0, v0, s[36:37]
	v_cmp_le_u32_e64 s[36:37], v50, v26
	s_nop 1
	v_cndmask_b32_e64 v14, 0, v2, s[36:37]
	v_cmp_le_u32_e64 s[36:37], v49, v26
	s_nop 1
	v_cndmask_b32_e64 v15, 0, v3, s[36:37]
	s_waitcnt lgkmcnt(0)
	v_mov_b32_e32 v36, v106
	v_mov_b32_e32 v37, v107
	v_mov_b32_e32 v38, v102
	v_mov_b32_e32 v39, v103
	v_mov_b32_e32 v52, v108
	v_mov_b32_e32 v53, v109
	v_mov_b32_e32 v54, v110
	v_mov_b32_e32 v55, v111
	v_mov_b32_e32 v56, v90
	v_mov_b32_e32 v57, v91
	v_mov_b32_e32 v58, v92
	v_mov_b32_e32 v59, v93
	v_mov_b32_e32 v60, v94
	v_mov_b32_e32 v61, v95
